# P6: sample-row K-slice tail GEMM runs before the main down GEMM so the fused-norm grid barrier also covers it; SEAM(7) grid barrier dropped; P3 K=128 chunk block hand-scheduled (batched LDS reads)
# baseline (speedup 1.0000x reference)
.LBB0_1201:
	s_min_u32 s2, s39, 58
	s_add_i32 s2, s2, 5
	s_mul_i32 s16, s2, 0x38000
	s_lshl_b32 s2, s2, 12
	s_mov_b32 s3, s17
	v_lshl_add_u64 v[82:83], v[102:103], 0, s[16:17]
	v_lshl_add_u64 v[86:87], v[104:105], 0, s[16:17]
	v_lshl_add_u64 v[90:91], v[108:109], 0, s[2:3]
	v_lshl_add_u64 v[94:95], v[106:107], 0, s[16:17]
	global_load_dwordx4 v[82:85], v[82:83], off
	s_nop 0
	global_load_dwordx4 v[86:89], v[86:87], off
	s_nop 0
	global_load_dwordx4 v[90:93], v[90:91], off
	s_nop 0
	global_load_dwordx4 v[94:97], v[94:95], off
	v_cndmask_b32_e64 v101, 0, 1, s[6:7]
	v_cmp_ne_u32_e64 s[2:3], 1, v101
	s_andn2_b64 vcc, exec, s[6:7]
	v_add_u32_e32 v129, 0x1000, v123
	s_cbranch_vccnz .LBB0_1203
	s_setprio 2
	v_add_u32_e32 v160, 0x1000, v123
	ds_read2_b64 v[128:131], v123 offset1:4
	ds_read2_b64 v[132:135], v160 offset0:32 offset1:36
	ds_read2_b64 v[136:139], v123 offset0:8 offset1:12
	ds_read2_b64 v[140:143], v160 offset0:40 offset1:44
	ds_read2_b64 v[144:147], v123 offset0:16 offset1:20
	ds_read2_b64 v[148:151], v160 offset0:48 offset1:52
	ds_read2_b64 v[152:155], v123 offset0:24 offset1:28
	ds_read2_b64 v[156:159], v160 offset0:56 offset1:60
	ds_read_u16 v161, v124 offset:19456
	ds_read_u16 v184, v124 offset:19728
	ds_read_u16 v185, v124 offset:20000
	ds_read_u16 v186, v124 offset:20272
	ds_read_u16 v179, v124 offset:20544
	ds_read_u16 v252, v124 offset:20816
	v_cvt_pk_bf16_f32 v162, v70, v71
	v_cvt_pk_bf16_f32 v163, v72, v73
	v_cvt_pk_bf16_f32 v164, v66, v67
	v_cvt_pk_bf16_f32 v165, v68, v69
	s_waitcnt lgkmcnt(13)
	s_nop 0
	v_mfma_f32_16x16x32_bf16 v[170:173], v[128:131], v[162:165], 0
	s_waitcnt lgkmcnt(12)
	v_mfma_f32_16x16x32_bf16 v[174:177], v[132:135], v[162:165], 0
	ds_read_u16 v253, v124 offset:21088
	ds_read_u16 v208, v124 offset:21360
	ds_read_b128 v[180:183], v125 offset:8704
	v_cvt_pk_bf16_f32 v166, v74, v75
	v_cvt_pk_bf16_f32 v167, v76, v77
	v_cvt_pk_bf16_f32 v168, v78, v79
	v_cvt_pk_bf16_f32 v169, v80, v81
	s_waitcnt lgkmcnt(14)
	s_nop 0
	v_mfma_f32_16x16x32_bf16 v[170:173], v[136:139], v[166:169], v[170:173]
	s_waitcnt lgkmcnt(13)
	v_mfma_f32_16x16x32_bf16 v[174:177], v[140:143], v[166:169], v[174:177]
	ds_read_b128 v[188:191], v122 offset:18944
	ds_read_b128 v[192:195], v125 offset:9984
	v_cvt_pk_bf16_f32 v162, v62, v63
	v_cvt_pk_bf16_f32 v163, v64, v65
	v_cvt_pk_bf16_f32 v164, v54, v55
	v_cvt_pk_bf16_f32 v165, v56, v57
	s_waitcnt lgkmcnt(14)
	s_nop 0
	v_mfma_f32_16x16x32_bf16 v[170:173], v[144:147], v[162:165], v[170:173]
	s_waitcnt lgkmcnt(13)
	v_mfma_f32_16x16x32_bf16 v[174:177], v[148:151], v[162:165], v[174:177]
	ds_read_b128 v[232:235], v122 offset:19008
	ds_read_b128 v[236:239], v125 offset:11264
	v_cvt_pk_bf16_f32 v166, v42, v43
	v_cvt_pk_bf16_f32 v167, v44, v45
	v_cvt_pk_bf16_f32 v168, v58, v59
	v_cvt_pk_bf16_f32 v169, v60, v61
	s_waitcnt lgkmcnt(14)
	s_nop 0
	v_mfma_f32_16x16x32_bf16 v[170:173], v[152:155], v[166:169], v[170:173]
	s_waitcnt lgkmcnt(13)
	v_mfma_f32_16x16x32_bf16 v[174:177], v[156:159], v[166:169], v[174:177]
	ds_read_b128 v[240:243], v122 offset:19072
	ds_read_b128 v[244:247], v126 offset:8704
	s_waitcnt lgkmcnt(7)
	v_lshl_or_b32 v248, v184, 16, v161
	v_lshl_or_b32 v249, v186, 16, v185
	v_lshl_or_b32 v250, v252, 16, v179
	v_lshl_or_b32 v251, v208, 16, v253
	ds_read_b128 v[128:131], v122 offset:19136
	ds_read_b128 v[132:135], v125 offset:13824
	s_waitcnt lgkmcnt(7)
	v_pk_mul_f32 v[72:73], v[72:73], v[190:191]
	v_pk_mul_f32 v[70:71], v[70:71], v[188:189]
	ds_read_b128 v[136:139], v122 offset:19200
	ds_read_b128 v[140:143], v125 offset:15104
	v_mfma_f32_16x16x32_bf16 v[70:73], v[180:183], v[248:251], v[70:73]
	s_waitcnt lgkmcnt(7)
	v_pk_mul_f32 v[68:69], v[68:69], v[234:235]
	v_pk_mul_f32 v[66:67], v[66:67], v[232:233]
	ds_read_b128 v[144:147], v122 offset:19264
	ds_read_b128 v[148:151], v125 offset:16384
	v_mfma_f32_16x16x32_bf16 v[66:69], v[192:195], v[248:251], v[66:69]
	s_waitcnt lgkmcnt(7)
	v_pk_mul_f32 v[76:77], v[76:77], v[242:243]
	v_pk_mul_f32 v[74:75], v[74:75], v[240:241]
	ds_read_b128 v[152:155], v122 offset:19328
	ds_read_b128 v[156:159], v127 offset:8704
	v_mfma_f32_16x16x32_bf16 v[74:77], v[236:239], v[248:251], v[74:77]
	s_waitcnt lgkmcnt(7)
	v_pk_mul_f32 v[80:81], v[80:81], v[130:131]
	v_pk_mul_f32 v[78:79], v[78:79], v[128:129]
	ds_read_b128 v[162:165], v122 offset:19392
	s_nop 0
	v_mfma_f32_16x16x32_bf16 v[78:81], v[244:247], v[248:251], v[78:81]
	s_waitcnt lgkmcnt(6)
	v_pk_mul_f32 v[64:65], v[64:65], v[138:139]
	v_pk_mul_f32 v[62:63], v[62:63], v[136:137]
	s_nop 1
	v_mfma_f32_16x16x32_bf16 v[62:65], v[132:135], v[248:251], v[62:65]
	s_waitcnt lgkmcnt(4)
	v_pk_mul_f32 v[56:57], v[56:57], v[146:147]
	v_pk_mul_f32 v[54:55], v[54:55], v[144:145]
	s_nop 1
	v_mfma_f32_16x16x32_bf16 v[54:57], v[140:143], v[248:251], v[54:57]
	s_waitcnt lgkmcnt(2)
	v_pk_mul_f32 v[44:45], v[44:45], v[154:155]
	v_pk_mul_f32 v[42:43], v[42:43], v[152:153]
	s_nop 1
	v_mfma_f32_16x16x32_bf16 v[42:45], v[148:151], v[248:251], v[42:45]
	s_waitcnt lgkmcnt(0)
	v_pk_mul_f32 v[60:61], v[60:61], v[164:165]
	v_pk_mul_f32 v[58:59], v[58:59], v[162:163]
	s_nop 1
	v_mfma_f32_16x16x32_bf16 v[58:61], v[156:159], v[248:251], v[58:61]
	v_cvt_pk_bf16_f32 v209, v170, v171
	v_cvt_pk_bf16_f32 v161, v172, v173
	v_cvt_pk_bf16_f32 v184, v174, v175
	v_cvt_pk_bf16_f32 v185, v176, v177
	v_add_co_u32_e32 v166, vcc, s24, v110
	s_nop 1
	v_addc_co_u32_e32 v167, vcc, 0, v111, vcc
	v_add_co_u32_e32 v168, vcc, s26, v110
	s_nop 1
	v_addc_co_u32_e32 v169, vcc, 0, v111, vcc
	global_store_short v[166:167], v209, off offset:-4096
	global_store_short_d16_hi v[166:167], v209, off offset:-2048
	global_store_short v[166:167], v161, off
	global_store_short_d16_hi v[166:167], v161, off offset:2048
	global_store_short v[168:169], v184, off offset:-4096
	global_store_short_d16_hi v[168:169], v184, off offset:-2048
	global_store_short v[168:169], v185, off
	global_store_short_d16_hi v[168:169], v185, off offset:2048
	s_setprio 0
.LBB0_1203:
	s_min_u32 s16, s39, 57
	s_add_i32 s40, s16, 6
	s_mul_i32 s16, s40, 0x38000
	s_waitcnt lgkmcnt(0)
	s_barrier
	s_waitcnt vmcnt(15)
	ds_write_b128 v99, v[2:5]
	s_waitcnt vmcnt(14)
	ds_write_b128 v119, v[10:13] offset:8704
	s_waitcnt vmcnt(13)
	ds_write_b128 v120, v[6:9] offset:18944
	s_waitcnt vmcnt(11)
	ds_write_b128 v121, v[22:25] offset:19456
	v_lshl_add_u64 v[2:3], v[102:103], 0, s[16:17]
	v_lshl_add_u64 v[6:7], v[104:105], 0, s[16:17]
	s_lshl_b32 s40, s40, 12
	s_mov_b32 s41, s17
	global_load_dwordx4 v[2:5], v[2:3], off
	s_nop 0
	global_load_dwordx4 v[10:13], v[6:7], off
	v_lshl_add_u64 v[6:7], v[108:109], 0, s[40:41]
	v_lshl_add_u64 v[22:23], v[106:107], 0, s[16:17]
	global_load_dwordx4 v[6:9], v[6:7], off
	s_nop 0
	global_load_dwordx4 v[22:25], v[22:23], off
	s_and_b64 vcc, exec, s[2:3]
	v_add_u32_e32 v128, 0x6800, v123
	v_add_u32_e32 v101, 0x7800, v123
	s_cbranch_vccnz .LBB0_1205
	s_setprio 2
	v_add_u32_e32 v160, 0x6800, v123
	v_add_u32_e32 v161, 0x7800, v123
	ds_read2_b64 v[128:131], v160 offset0:192 offset1:196
	ds_read2_b64 v[132:135], v161 offset0:224 offset1:228
	ds_read2_b64 v[136:139], v160 offset0:200 offset1:204
	ds_read2_b64 v[140:143], v161 offset0:232 offset1:236
	ds_read2_b64 v[144:147], v160 offset0:208 offset1:212
	ds_read2_b64 v[148:151], v161 offset0:240 offset1:244
	ds_read2_b64 v[152:155], v160 offset0:216 offset1:220
	ds_read2_b64 v[156:159], v161 offset0:248 offset1:252
	ds_read_u16 v184, v124 offset:47616
	ds_read_u16 v185, v124 offset:47888
	ds_read_u16 v186, v124 offset:48160
	ds_read_u16 v179, v124 offset:48432
	ds_read_u16 v252, v124 offset:48704
	ds_read_u16 v253, v124 offset:48976
	v_cvt_pk_bf16_f32 v162, v70, v71
	v_cvt_pk_bf16_f32 v163, v72, v73
	v_cvt_pk_bf16_f32 v164, v66, v67
	v_cvt_pk_bf16_f32 v165, v68, v69
	s_waitcnt lgkmcnt(13)
	s_nop 0
	v_mfma_f32_16x16x32_bf16 v[170:173], v[128:131], v[162:165], 0
	s_waitcnt lgkmcnt(12)
	v_mfma_f32_16x16x32_bf16 v[174:177], v[132:135], v[162:165], 0
	ds_read_u16 v208, v124 offset:49248
	ds_read_u16 v209, v124 offset:49520
	ds_read_b128 v[180:183], v125 offset:36864
	v_cvt_pk_bf16_f32 v166, v74, v75
	v_cvt_pk_bf16_f32 v167, v76, v77
	v_cvt_pk_bf16_f32 v168, v78, v79
	v_cvt_pk_bf16_f32 v169, v80, v81
	s_waitcnt lgkmcnt(14)
	s_nop 0
	v_mfma_f32_16x16x32_bf16 v[170:173], v[136:139], v[166:169], v[170:173]
	s_waitcnt lgkmcnt(13)
	v_mfma_f32_16x16x32_bf16 v[174:177], v[140:143], v[166:169], v[174:177]
	ds_read_b128 v[188:191], v122 offset:47104
	ds_read_b128 v[192:195], v125 offset:38144
	v_cvt_pk_bf16_f32 v162, v62, v63
	v_cvt_pk_bf16_f32 v163, v64, v65
	v_cvt_pk_bf16_f32 v164, v54, v55
	v_cvt_pk_bf16_f32 v165, v56, v57
	s_waitcnt lgkmcnt(14)
	s_nop 0
	v_mfma_f32_16x16x32_bf16 v[170:173], v[144:147], v[162:165], v[170:173]
	s_waitcnt lgkmcnt(13)
	v_mfma_f32_16x16x32_bf16 v[174:177], v[148:151], v[162:165], v[174:177]
	ds_read_b128 v[232:235], v122 offset:47168
	ds_read_b128 v[236:239], v125 offset:39424
	v_cvt_pk_bf16_f32 v166, v42, v43
	v_cvt_pk_bf16_f32 v167, v44, v45
	v_cvt_pk_bf16_f32 v168, v58, v59
	v_cvt_pk_bf16_f32 v169, v60, v61
	s_waitcnt lgkmcnt(14)
	s_nop 0
	v_mfma_f32_16x16x32_bf16 v[170:173], v[152:155], v[166:169], v[170:173]
	s_waitcnt lgkmcnt(13)
	v_mfma_f32_16x16x32_bf16 v[174:177], v[156:159], v[166:169], v[174:177]
	ds_read_b128 v[240:243], v122 offset:47232
	ds_read_b128 v[244:247], v126 offset:36864
	s_waitcnt lgkmcnt(7)
	v_lshl_or_b32 v248, v185, 16, v184
	v_lshl_or_b32 v249, v179, 16, v186
	v_lshl_or_b32 v250, v253, 16, v252
	v_lshl_or_b32 v251, v209, 16, v208
	ds_read_b128 v[128:131], v122 offset:47296
	ds_read_b128 v[132:135], v125 offset:41984
	s_waitcnt lgkmcnt(7)
	v_pk_mul_f32 v[72:73], v[72:73], v[190:191]
	v_pk_mul_f32 v[70:71], v[70:71], v[188:189]
	ds_read_b128 v[136:139], v122 offset:47360
	ds_read_b128 v[140:143], v125 offset:43264
	v_mfma_f32_16x16x32_bf16 v[70:73], v[180:183], v[248:251], v[70:73]
	s_waitcnt lgkmcnt(7)
	v_pk_mul_f32 v[68:69], v[68:69], v[234:235]
	v_pk_mul_f32 v[66:67], v[66:67], v[232:233]
	ds_read_b128 v[144:147], v122 offset:47424
	ds_read_b128 v[148:151], v125 offset:44544
	v_mfma_f32_16x16x32_bf16 v[66:69], v[192:195], v[248:251], v[66:69]
	s_waitcnt lgkmcnt(7)
	v_pk_mul_f32 v[76:77], v[76:77], v[242:243]
	v_pk_mul_f32 v[74:75], v[74:75], v[240:241]
	ds_read_b128 v[152:155], v122 offset:47488
	ds_read_b128 v[156:159], v127 offset:36864
	v_mfma_f32_16x16x32_bf16 v[74:77], v[236:239], v[248:251], v[74:77]
	s_waitcnt lgkmcnt(7)
	v_pk_mul_f32 v[80:81], v[80:81], v[130:131]
	v_pk_mul_f32 v[78:79], v[78:79], v[128:129]
	ds_read_b128 v[162:165], v122 offset:47552
	s_nop 0
	v_mfma_f32_16x16x32_bf16 v[78:81], v[244:247], v[248:251], v[78:81]
	s_waitcnt lgkmcnt(6)
	v_pk_mul_f32 v[64:65], v[64:65], v[138:139]
	v_pk_mul_f32 v[62:63], v[62:63], v[136:137]
	s_nop 1
	v_mfma_f32_16x16x32_bf16 v[62:65], v[132:135], v[248:251], v[62:65]
	s_waitcnt lgkmcnt(4)
	v_pk_mul_f32 v[56:57], v[56:57], v[146:147]
	v_pk_mul_f32 v[54:55], v[54:55], v[144:145]
	s_nop 1
	v_mfma_f32_16x16x32_bf16 v[54:57], v[140:143], v[248:251], v[54:57]
	s_waitcnt lgkmcnt(2)
	v_pk_mul_f32 v[44:45], v[44:45], v[154:155]
	v_pk_mul_f32 v[42:43], v[42:43], v[152:153]
	s_nop 1
	v_mfma_f32_16x16x32_bf16 v[42:45], v[148:151], v[248:251], v[42:45]
	s_waitcnt lgkmcnt(0)
	v_pk_mul_f32 v[60:61], v[60:61], v[164:165]
	v_pk_mul_f32 v[58:59], v[58:59], v[162:163]
	s_nop 1
	v_mfma_f32_16x16x32_bf16 v[58:61], v[156:159], v[248:251], v[58:61]
	v_cvt_pk_bf16_f32 v101, v170, v171
	v_cvt_pk_bf16_f32 v184, v172, v173
	v_cvt_pk_bf16_f32 v185, v174, v175
	v_cvt_pk_bf16_f32 v186, v176, v177
	v_add_co_u32_e32 v166, vcc, s28, v110
	s_nop 1
	v_addc_co_u32_e32 v167, vcc, 0, v111, vcc
	v_add_co_u32_e32 v168, vcc, s30, v110
	s_nop 1
	v_addc_co_u32_e32 v169, vcc, 0, v111, vcc
	global_store_short v[166:167], v101, off offset:-4096
	global_store_short_d16_hi v[166:167], v101, off offset:-2048
	global_store_short v[166:167], v184, off
	global_store_short_d16_hi v[166:167], v184, off offset:2048
	global_store_short v[168:169], v185, off offset:-4096
	global_store_short_d16_hi v[168:169], v185, off offset:-2048
	global_store_short v[168:169], v186, off
	global_store_short_d16_hi v[168:169], v186, off offset:2048
	s_setprio 0
.LBB0_1205:
	s_min_u32 s16, s39, 56
	s_add_i32 s40, s16, 7
	s_mul_i32 s16, s40, 0x38000
	s_lshl_b32 s40, s40, 12
	s_mov_b32 s41, s17
	s_waitcnt lgkmcnt(0)
	s_barrier
	s_waitcnt vmcnt(14)
	ds_write_b128 v99, v[18:21] offset:28160
	s_waitcnt vmcnt(13)
	ds_write_b128 v119, v[26:29] offset:36864
	s_waitcnt vmcnt(9)
	ds_write_b128 v120, v[46:49] offset:47104
	ds_write_b128 v121, v[38:41] offset:47616
	v_lshl_add_u64 v[18:19], v[102:103], 0, s[16:17]
	v_lshl_add_u64 v[26:27], v[104:105], 0, s[16:17]
	v_lshl_add_u64 v[38:39], v[108:109], 0, s[40:41]
	v_lshl_add_u64 v[40:41], v[106:107], 0, s[16:17]
	global_load_dwordx4 v[18:21], v[18:19], off
	s_nop 0
	global_load_dwordx4 v[26:29], v[26:27], off
	s_nop 0
	global_load_dwordx4 v[46:49], v[38:39], off
	s_nop 0
	global_load_dwordx4 v[38:41], v[40:41], off
	s_and_b64 vcc, exec, s[2:3]
	s_cbranch_vccnz .LBB0_1207
	s_setprio 2
	v_add_u32_e32 v160, 0x1000, v123
	ds_read2_b64 v[128:131], v123 offset1:4
	ds_read2_b64 v[132:135], v160 offset0:32 offset1:36
	ds_read2_b64 v[136:139], v123 offset0:8 offset1:12
	ds_read2_b64 v[140:143], v160 offset0:40 offset1:44
	ds_read2_b64 v[144:147], v123 offset0:16 offset1:20
	ds_read2_b64 v[148:151], v160 offset0:48 offset1:52
	ds_read2_b64 v[152:155], v123 offset0:24 offset1:28
	ds_read2_b64 v[156:159], v160 offset0:56 offset1:60
	ds_read_u16 v161, v124 offset:19456
	ds_read_u16 v184, v124 offset:19728
	ds_read_u16 v185, v124 offset:20000
	ds_read_u16 v186, v124 offset:20272
	ds_read_u16 v179, v124 offset:20544
	ds_read_u16 v252, v124 offset:20816
	v_cvt_pk_bf16_f32 v162, v70, v71
	v_cvt_pk_bf16_f32 v163, v72, v73
	v_cvt_pk_bf16_f32 v164, v66, v67
	v_cvt_pk_bf16_f32 v165, v68, v69
	s_waitcnt lgkmcnt(13)
	s_nop 0
	v_mfma_f32_16x16x32_bf16 v[170:173], v[128:131], v[162:165], 0
	s_waitcnt lgkmcnt(12)
	v_mfma_f32_16x16x32_bf16 v[174:177], v[132:135], v[162:165], 0
	ds_read_u16 v253, v124 offset:21088
	ds_read_u16 v208, v124 offset:21360
	ds_read_b128 v[180:183], v125 offset:8704
	v_cvt_pk_bf16_f32 v166, v74, v75
	v_cvt_pk_bf16_f32 v167, v76, v77
	v_cvt_pk_bf16_f32 v168, v78, v79
	v_cvt_pk_bf16_f32 v169, v80, v81
	s_waitcnt lgkmcnt(14)
	s_nop 0
	v_mfma_f32_16x16x32_bf16 v[170:173], v[136:139], v[166:169], v[170:173]
	s_waitcnt lgkmcnt(13)
	v_mfma_f32_16x16x32_bf16 v[174:177], v[140:143], v[166:169], v[174:177]
	ds_read_b128 v[188:191], v122 offset:18944
	ds_read_b128 v[192:195], v125 offset:9984
	v_cvt_pk_bf16_f32 v162, v62, v63
	v_cvt_pk_bf16_f32 v163, v64, v65
	v_cvt_pk_bf16_f32 v164, v54, v55
	v_cvt_pk_bf16_f32 v165, v56, v57
	s_waitcnt lgkmcnt(14)
	s_nop 0
	v_mfma_f32_16x16x32_bf16 v[170:173], v[144:147], v[162:165], v[170:173]
	s_waitcnt lgkmcnt(13)
	v_mfma_f32_16x16x32_bf16 v[174:177], v[148:151], v[162:165], v[174:177]
	ds_read_b128 v[232:235], v122 offset:19008
	ds_read_b128 v[236:239], v125 offset:11264
	v_cvt_pk_bf16_f32 v166, v42, v43
	v_cvt_pk_bf16_f32 v167, v44, v45
	v_cvt_pk_bf16_f32 v168, v58, v59
	v_cvt_pk_bf16_f32 v169, v60, v61
	s_waitcnt lgkmcnt(14)
	s_nop 0
	v_mfma_f32_16x16x32_bf16 v[170:173], v[152:155], v[166:169], v[170:173]
	s_waitcnt lgkmcnt(13)
	v_mfma_f32_16x16x32_bf16 v[174:177], v[156:159], v[166:169], v[174:177]
	ds_read_b128 v[240:243], v122 offset:19072
	ds_read_b128 v[244:247], v126 offset:8704
	s_waitcnt lgkmcnt(7)
	v_lshl_or_b32 v248, v184, 16, v161
	v_lshl_or_b32 v249, v186, 16, v185
	v_lshl_or_b32 v250, v252, 16, v179
	v_lshl_or_b32 v251, v208, 16, v253
	ds_read_b128 v[128:131], v122 offset:19136
	ds_read_b128 v[132:135], v125 offset:13824
	s_waitcnt lgkmcnt(7)
	v_pk_mul_f32 v[72:73], v[72:73], v[190:191]
	v_pk_mul_f32 v[70:71], v[70:71], v[188:189]
	ds_read_b128 v[136:139], v122 offset:19200
	ds_read_b128 v[140:143], v125 offset:15104
	v_mfma_f32_16x16x32_bf16 v[70:73], v[180:183], v[248:251], v[70:73]
	s_waitcnt lgkmcnt(7)
	v_pk_mul_f32 v[68:69], v[68:69], v[234:235]
	v_pk_mul_f32 v[66:67], v[66:67], v[232:233]
	ds_read_b128 v[144:147], v122 offset:19264
	ds_read_b128 v[148:151], v125 offset:16384
	v_mfma_f32_16x16x32_bf16 v[66:69], v[192:195], v[248:251], v[66:69]
	s_waitcnt lgkmcnt(7)
	v_pk_mul_f32 v[76:77], v[76:77], v[242:243]
	v_pk_mul_f32 v[74:75], v[74:75], v[240:241]
	ds_read_b128 v[152:155], v122 offset:19328
	ds_read_b128 v[156:159], v127 offset:8704
	v_mfma_f32_16x16x32_bf16 v[74:77], v[236:239], v[248:251], v[74:77]
	s_waitcnt lgkmcnt(7)
	v_pk_mul_f32 v[80:81], v[80:81], v[130:131]
	v_pk_mul_f32 v[78:79], v[78:79], v[128:129]
	ds_read_b128 v[162:165], v122 offset:19392
	s_nop 0
	v_mfma_f32_16x16x32_bf16 v[78:81], v[244:247], v[248:251], v[78:81]
	s_waitcnt lgkmcnt(6)
	v_pk_mul_f32 v[64:65], v[64:65], v[138:139]
	v_pk_mul_f32 v[62:63], v[62:63], v[136:137]
	s_nop 1
	v_mfma_f32_16x16x32_bf16 v[62:65], v[132:135], v[248:251], v[62:65]
	s_waitcnt lgkmcnt(4)
	v_pk_mul_f32 v[56:57], v[56:57], v[146:147]
	v_pk_mul_f32 v[54:55], v[54:55], v[144:145]
	s_nop 1
	v_mfma_f32_16x16x32_bf16 v[54:57], v[140:143], v[248:251], v[54:57]
	s_waitcnt lgkmcnt(2)
	v_pk_mul_f32 v[44:45], v[44:45], v[154:155]
	v_pk_mul_f32 v[42:43], v[42:43], v[152:153]
	s_nop 1
	v_mfma_f32_16x16x32_bf16 v[42:45], v[148:151], v[248:251], v[42:45]
	s_waitcnt lgkmcnt(0)
	v_pk_mul_f32 v[60:61], v[60:61], v[164:165]
	v_pk_mul_f32 v[58:59], v[58:59], v[162:163]
	s_nop 1
	v_mfma_f32_16x16x32_bf16 v[58:61], v[156:159], v[248:251], v[58:61]
	v_cvt_pk_bf16_f32 v209, v170, v171
	v_cvt_pk_bf16_f32 v161, v172, v173
	v_cvt_pk_bf16_f32 v184, v174, v175
	v_cvt_pk_bf16_f32 v185, v176, v177
	v_add_co_u32_e32 v166, vcc, s33, v110
	s_nop 1
	v_addc_co_u32_e32 v167, vcc, 0, v111, vcc
	v_add_co_u32_e32 v168, vcc, s35, v110
	s_nop 1
	v_addc_co_u32_e32 v169, vcc, 0, v111, vcc
	global_store_short v[166:167], v209, off offset:-4096
	global_store_short_d16_hi v[166:167], v209, off offset:-2048
	global_store_short v[166:167], v161, off
	global_store_short_d16_hi v[166:167], v161, off offset:2048
	global_store_short v[168:169], v184, off offset:-4096
	global_store_short_d16_hi v[168:169], v184, off offset:-2048
	global_store_short v[168:169], v185, off
	global_store_short_d16_hi v[168:169], v185, off offset:2048
	s_setprio 0
.LBB0_1207:
	s_min_u32 s16, s39, 55
	s_add_i32 s40, s16, 8
	s_mul_i32 s16, s40, 0x38000
	s_waitcnt lgkmcnt(0)
	s_barrier
	ds_write_b128 v99, v[30:33]
	ds_write_b128 v119, v[34:37] offset:8704
	s_waitcnt vmcnt(12)
	ds_write_b128 v120, v[50:53] offset:18944
	ds_write_b128 v121, v[14:17] offset:19456
	v_lshl_add_u64 v[14:15], v[102:103], 0, s[16:17]
	v_lshl_add_u64 v[16:17], v[104:105], 0, s[16:17]
	s_lshl_b32 s40, s40, 12
	s_mov_b32 s41, s17
	global_load_dwordx4 v[30:33], v[14:15], off
	global_load_dwordx4 v[34:37], v[16:17], off
	v_lshl_add_u64 v[14:15], v[108:109], 0, s[40:41]
	v_lshl_add_u64 v[16:17], v[106:107], 0, s[16:17]
	global_load_dwordx4 v[50:53], v[14:15], off
	s_nop 0
	global_load_dwordx4 v[14:17], v[16:17], off
	s_and_b64 vcc, exec, s[2:3]
	s_cbranch_vccnz .LBB0_1209
	s_setprio 2
	v_add_u32_e32 v160, 0x6800, v123
	v_add_u32_e32 v161, 0x7800, v123
	ds_read2_b64 v[128:131], v160 offset0:192 offset1:196
	ds_read2_b64 v[132:135], v161 offset0:224 offset1:228
	ds_read2_b64 v[136:139], v160 offset0:200 offset1:204
	ds_read2_b64 v[140:143], v161 offset0:232 offset1:236
	ds_read2_b64 v[144:147], v160 offset0:208 offset1:212
	ds_read2_b64 v[148:151], v161 offset0:240 offset1:244
	ds_read2_b64 v[152:155], v160 offset0:216 offset1:220
	ds_read2_b64 v[156:159], v161 offset0:248 offset1:252
	ds_read_u16 v184, v124 offset:47616
	ds_read_u16 v185, v124 offset:47888
	ds_read_u16 v186, v124 offset:48160
	ds_read_u16 v179, v124 offset:48432
	ds_read_u16 v252, v124 offset:48704
	ds_read_u16 v253, v124 offset:48976
	v_cvt_pk_bf16_f32 v162, v70, v71
	v_cvt_pk_bf16_f32 v163, v72, v73
	v_cvt_pk_bf16_f32 v164, v66, v67
	v_cvt_pk_bf16_f32 v165, v68, v69
	s_waitcnt lgkmcnt(13)
	s_nop 0
	v_mfma_f32_16x16x32_bf16 v[170:173], v[128:131], v[162:165], 0
	s_waitcnt lgkmcnt(12)
	v_mfma_f32_16x16x32_bf16 v[174:177], v[132:135], v[162:165], 0
	ds_read_u16 v208, v124 offset:49248
	ds_read_u16 v209, v124 offset:49520
	ds_read_b128 v[180:183], v125 offset:36864
	v_cvt_pk_bf16_f32 v166, v74, v75
	v_cvt_pk_bf16_f32 v167, v76, v77
	v_cvt_pk_bf16_f32 v168, v78, v79
	v_cvt_pk_bf16_f32 v169, v80, v81
	s_waitcnt lgkmcnt(14)
	s_nop 0
	v_mfma_f32_16x16x32_bf16 v[170:173], v[136:139], v[166:169], v[170:173]
	s_waitcnt lgkmcnt(13)
	v_mfma_f32_16x16x32_bf16 v[174:177], v[140:143], v[166:169], v[174:177]
	ds_read_b128 v[188:191], v122 offset:47104
	ds_read_b128 v[192:195], v125 offset:38144
	v_cvt_pk_bf16_f32 v162, v62, v63
	v_cvt_pk_bf16_f32 v163, v64, v65
	v_cvt_pk_bf16_f32 v164, v54, v55
	v_cvt_pk_bf16_f32 v165, v56, v57
	s_waitcnt lgkmcnt(14)
	s_nop 0
	v_mfma_f32_16x16x32_bf16 v[170:173], v[144:147], v[162:165], v[170:173]
	s_waitcnt lgkmcnt(13)
	v_mfma_f32_16x16x32_bf16 v[174:177], v[148:151], v[162:165], v[174:177]
	ds_read_b128 v[232:235], v122 offset:47168
	ds_read_b128 v[236:239], v125 offset:39424
	v_cvt_pk_bf16_f32 v166, v42, v43
	v_cvt_pk_bf16_f32 v167, v44, v45
	v_cvt_pk_bf16_f32 v168, v58, v59
	v_cvt_pk_bf16_f32 v169, v60, v61
	s_waitcnt lgkmcnt(14)
	s_nop 0
	v_mfma_f32_16x16x32_bf16 v[170:173], v[152:155], v[166:169], v[170:173]
	s_waitcnt lgkmcnt(13)
	v_mfma_f32_16x16x32_bf16 v[174:177], v[156:159], v[166:169], v[174:177]
	ds_read_b128 v[240:243], v122 offset:47232
	ds_read_b128 v[244:247], v126 offset:36864
	s_waitcnt lgkmcnt(7)
	v_lshl_or_b32 v248, v185, 16, v184
	v_lshl_or_b32 v249, v179, 16, v186
	v_lshl_or_b32 v250, v253, 16, v252
	v_lshl_or_b32 v251, v209, 16, v208
	ds_read_b128 v[128:131], v122 offset:47296
	ds_read_b128 v[132:135], v125 offset:41984
	s_waitcnt lgkmcnt(7)
	v_pk_mul_f32 v[72:73], v[72:73], v[190:191]
	v_pk_mul_f32 v[70:71], v[70:71], v[188:189]
	ds_read_b128 v[136:139], v122 offset:47360
	ds_read_b128 v[140:143], v125 offset:43264
	v_mfma_f32_16x16x32_bf16 v[70:73], v[180:183], v[248:251], v[70:73]
	s_waitcnt lgkmcnt(7)
	v_pk_mul_f32 v[68:69], v[68:69], v[234:235]
	v_pk_mul_f32 v[66:67], v[66:67], v[232:233]
	ds_read_b128 v[144:147], v122 offset:47424
	ds_read_b128 v[148:151], v125 offset:44544
	v_mfma_f32_16x16x32_bf16 v[66:69], v[192:195], v[248:251], v[66:69]
	s_waitcnt lgkmcnt(7)
	v_pk_mul_f32 v[76:77], v[76:77], v[242:243]
	v_pk_mul_f32 v[74:75], v[74:75], v[240:241]
	ds_read_b128 v[152:155], v122 offset:47488
	ds_read_b128 v[156:159], v127 offset:36864
	v_mfma_f32_16x16x32_bf16 v[74:77], v[236:239], v[248:251], v[74:77]
	s_waitcnt lgkmcnt(7)
	v_pk_mul_f32 v[80:81], v[80:81], v[130:131]
	v_pk_mul_f32 v[78:79], v[78:79], v[128:129]
	ds_read_b128 v[162:165], v122 offset:47552
	s_nop 0
	v_mfma_f32_16x16x32_bf16 v[78:81], v[244:247], v[248:251], v[78:81]
	s_waitcnt lgkmcnt(6)
	v_pk_mul_f32 v[64:65], v[64:65], v[138:139]
	v_pk_mul_f32 v[62:63], v[62:63], v[136:137]
	s_nop 1
	v_mfma_f32_16x16x32_bf16 v[62:65], v[132:135], v[248:251], v[62:65]
	s_waitcnt lgkmcnt(4)
	v_pk_mul_f32 v[56:57], v[56:57], v[146:147]
	v_pk_mul_f32 v[54:55], v[54:55], v[144:145]
	s_nop 1
	v_mfma_f32_16x16x32_bf16 v[54:57], v[140:143], v[248:251], v[54:57]
	s_waitcnt lgkmcnt(2)
	v_pk_mul_f32 v[44:45], v[44:45], v[154:155]
	v_pk_mul_f32 v[42:43], v[42:43], v[152:153]
	s_nop 1
	v_mfma_f32_16x16x32_bf16 v[42:45], v[148:151], v[248:251], v[42:45]
	s_waitcnt lgkmcnt(0)
	v_pk_mul_f32 v[60:61], v[60:61], v[164:165]
	v_pk_mul_f32 v[58:59], v[58:59], v[162:163]
	s_nop 1
	v_mfma_f32_16x16x32_bf16 v[58:61], v[156:159], v[248:251], v[58:61]
	v_cvt_pk_bf16_f32 v101, v170, v171
	v_cvt_pk_bf16_f32 v184, v172, v173
	v_cvt_pk_bf16_f32 v185, v174, v175
	v_cvt_pk_bf16_f32 v186, v176, v177
	v_add_co_u32_e32 v166, vcc, s37, v110
	s_nop 1
	v_addc_co_u32_e32 v167, vcc, 0, v111, vcc
	v_add_co_u32_e32 v168, vcc, s38, v110
	s_nop 1
	v_addc_co_u32_e32 v169, vcc, 0, v111, vcc
	global_store_short v[166:167], v101, off offset:-4096
	global_store_short_d16_hi v[166:167], v101, off offset:-2048
	global_store_short v[166:167], v184, off
	global_store_short_d16_hi v[166:167], v184, off offset:2048
	global_store_short v[168:169], v185, off offset:-4096
	global_store_short_d16_hi v[168:169], v185, off offset:-2048
	global_store_short v[168:169], v186, off
	global_store_short_d16_hi v[168:169], v186, off offset:2048
	s_setprio 0

.LBB0_1629:
	s_mov_b32 s98, 0
	s_cmp_lt_i32 s92, 8
	s_cselect_b64 s[0:1], -1, 0
	s_and_b64 s[0:1], s[0:1], s[2:3]
	s_andn2_b64 vcc, exec, s[0:1]
	s_cbranch_vccnz .LBB0_1777
.Lp6_reenter:
	s_add_u32 s50, s46, 0x1500000
	s_addc_u32 s51, s47, 0
	s_add_u32 s52, s46, 0x7100000
	s_addc_u32 s53, s47, 0
	s_add_u32 s8, s46, 0x4f00000
	s_addc_u32 s9, s47, 0
	s_cmpk_lg_i32 s91, 0x100
	s_cselect_b64 s[4:5], -1, 0
	s_xor_b64 s[6:7], s[70:71], -1
	s_or_b64 s[4:5], s[6:7], s[4:5]
	s_mov_b64 s[2:3], -1
	s_and_b64 vcc, exec, s[4:5]
	v_and_b32_e32 v194, 15, v1
	v_lshrrev_b32_e32 v193, 1, v1
	v_lshlrev_b32_e32 v157, 6, v1
	s_cbranch_vccz .LBB0_1660
	v_readfirstlane_b32 s4, v1
	v_and_b32_e32 v156, 15, v1
	v_and_b32_e32 v190, 24, v193
	v_and_b32_e32 v191, 0x3c0, v157
	v_and_b32_e32 v192, 32, v178
	s_cmp_lg_u32 s98, 0
	s_cbranch_scc1 .Lp6_main
	s_mov_b32 s98, 1
	s_branch .LBB0_1757
.Lp6_main:
	s_cmpk_gt_i32 s85, 0xff
	s_cbranch_scc1 .LBB0_1659
	s_ashr_i32 s22, s85, 31
	s_lshr_b32 s2, s22, 29
	s_add_i32 s7, s85, s2
	s_and_b32 s2, s7, -8
	s_sub_i32 s5, s85, s2
	s_cmp_gt_i32 s5, -1
	s_cbranch_scc0 .LBB0_1634
	s_lshl_b32 s6, s5, 5
	s_ashr_i32 s3, s7, 3
	s_cbranch_execz .LBB0_1635
	s_branch .LBB0_1636

.LBB0_1756:
	s_cmp_eq_u32 s98, 2
	s_cbranch_scc1 .Lp6_done
	v_mov_b32_e32 v156, v194

.Lp6_after_tail:
	s_cmp_eq_u32 s98, 1
	s_cbranch_scc0 .LBB0_1777
	s_mov_b32 s98, 2
	v_lshlrev_b32_e32 v178, 2, v1
	s_branch .Lp6_reenter
.Lp6_done:
.LBB0_1777:
	s_cmp_gt_i32 s93, 8
	s_cselect_b64 s[2:3], -1, 0
	s_and_b64 s[0:1], s[0:1], s[2:3]
	s_andn2_b64 vcc, exec, s[0:1]
	s_cbranch_vccnz .LBB0_1841
	s_cmp_eq_u32 s98, 2
	s_cbranch_scc1 .LBB0_1841
	s_cmp_eq_u32 s95, 0
	s_cbranch_scc1 .LBB0_1790
	s_waitcnt vmcnt(0)
	v_lshrrev_b32_e32 v2, 20, v0
	v_lshrrev_b32_e32 v0, 10, v0
	v_or_b32_e32 v0, v0, v2
	s_movk_i32 s0, 0x3ff
	v_and_or_b32 v0, v0, s0, v1
	v_cmp_eq_u32_e32 vcc, 0, v0
	s_waitcnt lgkmcnt(0)
	s_barrier
	s_and_saveexec_b64 s[0:1], vcc
	s_cbranch_execz .LBB0_1789
	v_readlane_b32 s4, v255, 4
	v_readlane_b32 s5, v255, 5
	buffer_wbl2 sc1
	s_load_dwordx2 s[4:5], s[4:5], 0x58
	v_mov_b32_e32 v2, 0
	s_mov_b64 s[6:7], exec
	v_mbcnt_lo_u32_b32 v1, s6, 0
	v_mbcnt_hi_u32_b32 v1, s7, v1
	s_waitcnt lgkmcnt(0)
	global_load_dword v0, v2, s[4:5] offset:40
	v_cmp_eq_u32_e32 vcc, 0, v1
	s_and_saveexec_b64 s[8:9], vcc
	s_cbranch_execz .LBB0_1782
	s_bcnt1_i32_b64 s6, s[6:7]
	v_mov_b32_e32 v3, s6
	global_atomic_add v3, v2, v3, s[4:5] offset:32 sc0

	.amdhsa_kernel _Z9hymba_fwd4Args
		.amdhsa_group_segment_fixed_size 0
		.amdhsa_private_segment_fixed_size 0
		.amdhsa_kernarg_size 424
		.amdhsa_user_sgpr_count 2
		.amdhsa_user_sgpr_dispatch_ptr 0
		.amdhsa_user_sgpr_queue_ptr 0
		.amdhsa_user_sgpr_kernarg_segment_ptr 1
		.amdhsa_user_sgpr_dispatch_id 0
		.amdhsa_user_sgpr_kernarg_preload_length 0
		.amdhsa_user_sgpr_kernarg_preload_offset 0
		.amdhsa_user_sgpr_private_segment_size 0
		.amdhsa_uses_dynamic_stack 0
		.amdhsa_enable_private_segment 0
		.amdhsa_system_sgpr_workgroup_id_x 1
		.amdhsa_system_sgpr_workgroup_id_y 0
		.amdhsa_system_sgpr_workgroup_id_z 0
		.amdhsa_system_sgpr_workgroup_info 0
		.amdhsa_system_vgpr_workitem_id 2
		.amdhsa_next_free_vgpr 256
		.amdhsa_next_free_sgpr 102
		.amdhsa_accum_offset 256
		.amdhsa_reserve_vcc 1
		.amdhsa_float_round_mode_32 0
		.amdhsa_float_round_mode_16_64 0
		.amdhsa_float_denorm_mode_32 3
		.amdhsa_float_denorm_mode_16_64 3
		.amdhsa_dx10_clamp 1
		.amdhsa_ieee_mode 1
		.amdhsa_fp16_overflow 0
		.amdhsa_tg_split 0
		.amdhsa_exception_fp_ieee_invalid_op 0
		.amdhsa_exception_fp_denorm_src 0
		.amdhsa_exception_fp_ieee_div_zero 0
		.amdhsa_exception_fp_ieee_overflow 0
		.amdhsa_exception_fp_ieee_underflow 0
		.amdhsa_exception_fp_ieee_inexact 0
		.amdhsa_exception_int_div_zero 0
	.end_amdhsa_kernel

amdhsa.kernels:
  - .agpr_count:     0
    .args:
      - .offset:         0
        .size:           168
        .value_kind:     by_value
      - .offset:         168
        .size:           4
        .value_kind:     hidden_block_count_x
      - .offset:         172
        .size:           4
        .value_kind:     hidden_block_count_y
      - .offset:         176
        .size:           4
        .value_kind:     hidden_block_count_z
      - .offset:         180
        .size:           2
        .value_kind:     hidden_group_size_x
      - .offset:         182
        .size:           2
        .value_kind:     hidden_group_size_y
      - .offset:         184
        .size:           2
        .value_kind:     hidden_group_size_z
      - .offset:         186
        .size:           2
        .value_kind:     hidden_remainder_x
      - .offset:         188
        .size:           2
        .value_kind:     hidden_remainder_y
      - .offset:         190
        .size:           2
        .value_kind:     hidden_remainder_z
      - .offset:         208
        .size:           8
        .value_kind:     hidden_global_offset_x
      - .offset:         216
        .size:           8
        .value_kind:     hidden_global_offset_y
      - .offset:         224
        .size:           8
        .value_kind:     hidden_global_offset_z
      - .offset:         232
        .size:           2
        .value_kind:     hidden_grid_dims
      - .offset:         256
        .size:           8
        .value_kind:     hidden_multigrid_sync_arg
      - .offset:         288
        .size:           4
        .value_kind:     hidden_dynamic_lds_size
    .group_segment_fixed_size: 0
    .kernarg_segment_align: 8
    .kernarg_segment_size: 424
    .language:       OpenCL C
    .language_version:
      - 2
      - 0
    .max_flat_workgroup_size: 512
    .name:           _Z9hymba_fwd4Args
    .private_segment_fixed_size: 0
    .sgpr_count:     108
    .sgpr_spill_count: 48
    .symbol:         _Z9hymba_fwd4Args.kd
    .uniform_work_group_size: 1
    .uses_dynamic_stack: false
    .vgpr_count:     256
    .vgpr_spill_count: 0
    .wavefront_size: 64
